# natten masked tile: removed PV MFMAs and row-sum adds on statically masked (always zero) key blocks
# baseline (speedup 1.0000x reference)
.LBB0_391:
	v_sub_f32_e32 v24, v27, v221
	v_exp_f32_e32 v167, v24
	v_sub_f32_e32 v24, v26, v221
	v_exp_f32_e32 v168, v24
	v_sub_f32_e32 v24, v29, v221
	v_exp_f32_e32 v169, v24
	v_sub_f32_e32 v24, v28, v221
	v_exp_f32_e32 v170, v24
	v_sub_f32_e32 v24, v31, v221
	v_exp_f32_e32 v171, v24
	v_sub_f32_e32 v24, v30, v221
	v_exp_f32_e32 v172, v24
	v_sub_f32_e32 v24, v33, v221
	v_exp_f32_e32 v173, v24
	v_sub_f32_e32 v24, v32, v221
	v_exp_f32_e32 v174, v24
	v_sub_f32_e32 v24, v164, v221
	v_exp_f32_e32 v175, v24
	v_sub_f32_e32 v24, v162, v221
	v_lshl_add_u32 v180, s3, 1, v216
	v_exp_f32_e32 v176, v24
	v_sub_f32_e32 v24, v177, v221
	v_exp_f32_e32 v177, v24
	v_sub_f32_e32 v24, v178, v221
	v_add_u32_e32 v162, 0x3000, v180
	v_exp_f32_e32 v178, v24
	ds_read2_b64 v[24:27], v162 offset0:128 offset1:130
	v_sub_f32_e32 v28, v179, v221
	v_exp_f32_e32 v179, v28
	v_cvt_pk_bf16_f32 v28, v167, v168
	v_cvt_pk_bf16_f32 v29, v169, v170
	v_cvt_pk_bf16_f32 v30, v171, v172
	v_cvt_pk_bf16_f32 v31, v173, v174
	v_add_u32_e32 v164, 0x4000, v180
	ds_read2_b64 v[186:189], v164 offset0:192 offset1:194
	s_waitcnt lgkmcnt(1)
	v_mfma_f32_32x32x16_bf16 v[50:65], v[24:27], v[28:31], v[50:65]
	v_sub_f32_e32 v24, v166, v221
	v_exp_f32_e32 v180, v24
	v_sub_f32_e32 v24, v181, v221
	v_exp_f32_e32 v181, v24
	v_sub_f32_e32 v24, v182, v221
	v_exp_f32_e32 v182, v24
	ds_read2_b64 v[24:27], v162 offset0:132 offset1:134
	s_waitcnt lgkmcnt(1)
	v_mfma_f32_32x32x16_bf16 v[34:49], v[186:189], v[28:31], v[34:49]
	v_sub_f32_e32 v28, v183, v221
	v_exp_f32_e32 v183, v28
	v_cvt_pk_bf16_f32 v28, v175, v176
	v_cvt_pk_bf16_f32 v29, v177, v178
	v_cvt_pk_bf16_f32 v30, v179, v180
	v_cvt_pk_bf16_f32 v31, v181, v182
	ds_read2_b64 v[222:225], v164 offset0:196 offset1:198
	v_sub_f32_e32 v23, v23, v221
	s_waitcnt lgkmcnt(1)
	v_mfma_f32_32x32x16_bf16 v[50:65], v[24:27], v[28:31], v[50:65]
	v_sub_f32_e32 v24, v184, v221
	v_exp_f32_e32 v184, v24
	v_sub_f32_e32 v24, v185, v221
	v_exp_f32_e32 v185, v24
	ds_read2_b64 v[24:27], v162 offset0:136 offset1:138
	v_exp_f32_e32 v186, v23
	v_sub_f32_e32 v23, 0xff800000, v221
	v_exp_f32_e32 v187, v23
	s_waitcnt lgkmcnt(1)
	v_mfma_f32_32x32x16_bf16 v[34:49], v[222:225], v[28:31], v[34:49]
	v_cvt_pk_bf16_f32 v28, v183, v184
	v_cvt_pk_bf16_f32 v29, v185, v186
	v_cvt_pk_bf16_f32 v30, v187, v187
	v_mov_b32_e32 v31, v30
	v_mov_b32_e32 v188, 0xff800000
	s_waitcnt lgkmcnt(0)
	v_mfma_f32_32x32x16_bf16 v[50:65], v[24:27], v[28:31], v[50:65]
	ds_read2_b64 v[24:27], v164 offset0:200 offset1:202
	s_waitcnt lgkmcnt(0)
	v_mfma_f32_32x32x16_bf16 v[34:49], v[24:27], v[28:31], v[34:49]
	v_mov_b32_e32 v23, 0xff800000
	ds_read_b32 v189, v218
	ds_read_b32 v188, v218 offset:4
	ds_read_b32 v209, v218 offset:8
	ds_read_b32 v208, v218 offset:12
	ds_read_b32 v225, v218 offset:32
	ds_read_b32 v223, v218 offset:36
	ds_read_b32 v233, v218 offset:40
	ds_read_b32 v231, v218 offset:44
	ds_read_b32 v237, v218 offset:64
	ds_read_b32 v212, v218 offset:68
	ds_read_b32 v227, v218 offset:72
	ds_read_b32 v224, v218 offset:76
	ds_read_b32 v235, v218 offset:96
	ds_read_b32 v229, v218 offset:100
	ds_read_b32 v234, v218 offset:104
	ds_read_b32 v226, v218 offset:108
	ds_read_b32 v230, v218 offset:128
	ds_read_b32 v228, v218 offset:132
	ds_read_b32 v236, v218 offset:136
	ds_read_b32 v232, v218 offset:140
	s_waitcnt lgkmcnt(10)
	v_add_f32_e32 v189, v18, v189
	v_add_f32_e32 v188, v19, v188
	v_add_f32_e32 v209, v20, v209
	v_add_f32_e32 v208, v21, v208
	v_add_f32_e32 v225, v2, v225
	v_add_f32_e32 v223, v3, v223
	v_add_f32_e32 v233, v4, v233
	v_add_f32_e32 v231, v5, v231
	v_add_f32_e32 v237, v6, v237
	v_add_f32_e32 v212, v7, v212
	s_waitcnt lgkmcnt(0)
	v_add_f32_e32 v227, v8, v227
	v_add_f32_e32 v224, v9, v224
	v_add_f32_e32 v235, v10, v235
	v_add_f32_e32 v229, v11, v229
	v_add_f32_e32 v234, v12, v234
	v_add_f32_e32 v226, v13, v226
	v_add_f32_e32 v230, v14, v230
	v_add_f32_e32 v228, v15, v228
	v_add_f32_e32 v236, v16, v236
	v_add_f32_e32 v232, v17, v232
	v_cndmask_b32_e64 v189, v23, v189, s[44:45]
	v_cndmask_b32_e64 v188, v23, v188, s[46:47]
	v_cndmask_b32_e64 v209, v23, v209, s[48:49]
	v_cndmask_b32_e64 v208, v23, v208, s[50:51]
	v_cndmask_b32_e64 v225, v23, v225, s[52:53]
	v_cndmask_b32_e64 v223, v23, v223, s[54:55]
	v_cndmask_b32_e64 v233, v23, v233, s[56:57]
	v_cndmask_b32_e64 v231, v23, v231, s[58:59]
	v_cndmask_b32_e64 v237, v23, v237, s[60:61]
	v_cndmask_b32_e64 v212, v23, v212, s[62:63]
	v_cndmask_b32_e64 v227, v23, v227, s[64:65]
	v_cndmask_b32_e64 v224, v23, v224, s[66:67]
	v_cndmask_b32_e64 v235, v23, v235, s[68:69]
	v_cndmask_b32_e64 v229, v23, v229, s[70:71]
	v_cndmask_b32_e64 v234, v23, v234, s[72:73]
	v_cndmask_b32_e64 v226, v23, v226, s[74:75]
	v_cndmask_b32_e64 v230, v23, v230, s[76:77]
	v_cndmask_b32_e64 v228, v23, v228, s[78:79]
	v_cndmask_b32_e64 v236, v23, v236, s[80:81]
	v_cndmask_b32_e64 v232, v23, v232, s[82:83]
	v_max3_f32 v2, v189, s88, v188
	v_max3_f32 v2, v2, v209, v208
	v_max3_f32 v2, v2, v225, v223
	v_max3_f32 v2, v2, v233, v231
	v_max3_f32 v2, v2, v237, v212
	v_max3_f32 v2, v2, v227, v224
	v_max3_f32 v2, v2, v235, v229
	v_max3_f32 v2, v2, v234, v226
	v_max3_f32 v2, v2, v230, v228
	v_max3_f32 v2, v2, v236, v232
	ds_bpermute_b32 v3, v22, v2
	v_mov_b64_e32 v[18:19], v[82:83]
	v_mov_b64_e32 v[20:21], v[84:85]
	v_mov_b64_e32 v[22:23], v[86:87]
	v_mov_b64_e32 v[24:25], v[88:89]
	s_waitcnt lgkmcnt(0)
	v_max_f32_e32 v3, v3, v3
	v_max_f32_e32 v222, v2, v3
	v_mov_b64_e32 v[2:3], v[66:67]
	v_cmp_gt_f32_e32 vcc, v222, v0
	v_mov_b64_e32 v[4:5], v[68:69]
	v_mov_b64_e32 v[6:7], v[70:71]
	v_mov_b64_e32 v[8:9], v[72:73]
	v_mov_b64_e32 v[10:11], v[74:75]
	v_mov_b64_e32 v[12:13], v[76:77]
	v_mov_b64_e32 v[14:15], v[78:79]
	v_mov_b64_e32 v[16:17], v[80:81]
	v_mov_b64_e32 v[26:27], v[90:91]
	v_mov_b64_e32 v[28:29], v[92:93]
	v_mov_b64_e32 v[30:31], v[94:95]
	v_mov_b64_e32 v[32:33], v[96:97]
	v_mov_b32_e32 v238, v219
	v_mov_b32_e32 v166, v0
	s_cbranch_vccz .LBB0_433
	v_max_f32_e32 v2, v222, v222
	v_max_f32_e32 v3, v0, v0
	v_max_f32_e32 v166, v3, v2
	v_sub_f32_e32 v2, v0, v166
	v_exp_f32_e32 v2, v2
	s_nop 0
	v_mul_f32_e32 v238, v219, v2
	v_pk_mul_f32 v[32:33], v[96:97], v[2:3] op_sel_hi:[1,0]
	v_pk_mul_f32 v[30:31], v[94:95], v[2:3] op_sel_hi:[1,0]
	v_pk_mul_f32 v[28:29], v[92:93], v[2:3] op_sel_hi:[1,0]
	v_pk_mul_f32 v[26:27], v[90:91], v[2:3] op_sel_hi:[1,0]
	v_pk_mul_f32 v[24:25], v[88:89], v[2:3] op_sel_hi:[1,0]
	v_pk_mul_f32 v[22:23], v[86:87], v[2:3] op_sel_hi:[1,0]
	v_pk_mul_f32 v[20:21], v[84:85], v[2:3] op_sel_hi:[1,0]
	v_pk_mul_f32 v[18:19], v[82:83], v[2:3] op_sel_hi:[1,0]
	v_pk_mul_f32 v[16:17], v[80:81], v[2:3] op_sel_hi:[1,0]
	v_pk_mul_f32 v[14:15], v[78:79], v[2:3] op_sel_hi:[1,0]
	v_pk_mul_f32 v[12:13], v[76:77], v[2:3] op_sel_hi:[1,0]
	v_pk_mul_f32 v[10:11], v[74:75], v[2:3] op_sel_hi:[1,0]
	v_pk_mul_f32 v[8:9], v[72:73], v[2:3] op_sel_hi:[1,0]
	v_pk_mul_f32 v[6:7], v[70:71], v[2:3] op_sel_hi:[1,0]
	v_pk_mul_f32 v[4:5], v[68:69], v[2:3] op_sel_hi:[1,0]
	v_pk_mul_f32 v[2:3], v[66:67], v[2:3] op_sel_hi:[1,0]
.LBB0_433:
	v_add_f32_e32 v167, 0, v167
	v_add_f32_e32 v167, v168, v167
	v_add_f32_e32 v167, v169, v167
	v_add_f32_e32 v167, v170, v167
	v_add_f32_e32 v167, v171, v167
	v_add_f32_e32 v167, v172, v167
	v_add_f32_e32 v167, v173, v167
	v_add_f32_e32 v167, v174, v167
	v_add_f32_e32 v167, v175, v167
	v_add_f32_e32 v167, v176, v167
	v_add_f32_e32 v167, v177, v167
	v_add_f32_e32 v167, v178, v167
	v_add_f32_e32 v167, v179, v167
	v_add_f32_e32 v167, v180, v167
	v_add_f32_e32 v167, v181, v167
	v_add_f32_e32 v167, v182, v167
	v_add_f32_e32 v167, v183, v167
	v_add_f32_e32 v167, v184, v167
	v_add_f32_e32 v167, v185, v167
	v_add_f32_e32 v167, v186, v167
	v_sub_f32_e32 v168, 0xff800000, v166
	v_exp_f32_e32 v172, v168
	v_sub_f32_e32 v168, v188, v166
	v_exp_f32_e32 v180, v168
	v_sub_f32_e32 v168, v209, v166
	v_exp_f32_e32 v181, v168
	v_sub_f32_e32 v168, v208, v166
	v_exp_f32_e32 v182, v168
	v_sub_f32_e32 v168, v225, v166
	v_add_f32_e32 v222, v165, v167
	v_add_f32_e32 v165, 0, v172
	v_exp_f32_e32 v183, v168
	v_sub_f32_e32 v168, v223, v166
	v_exp_f32_e32 v184, v168
	v_sub_f32_e32 v168, v233, v166
	v_exp_f32_e32 v185, v168
	v_sub_f32_e32 v168, v231, v166
	v_exp_f32_e32 v186, v168
	v_sub_f32_e32 v168, v237, v166
	v_exp_f32_e32 v187, v168
	ds_read2_b64 v[168:171], v162 offset0:128 offset1:130
	ds_read2_b64 v[176:179], v164 offset0:192 offset1:194
	v_sub_f32_e32 v173, v212, v166
	v_cvt_pk_bf16_f32 v172, v172, v172
	v_exp_f32_e32 v188, v173
	v_mov_b32_e32 v173, v172
	v_mov_b32_e32 v174, v172
	v_mov_b32_e32 v175, v172
	v_sub_f32_e32 v167, v189, v166
	v_exp_f32_e32 v167, v167
	s_waitcnt lgkmcnt(1)
	v_sub_f32_e32 v168, v227, v166
	v_exp_f32_e32 v189, v168
	v_sub_f32_e32 v168, v224, v166
	v_exp_f32_e32 v202, v168
	ds_read2_b64 v[168:171], v162 offset0:132 offset1:134
	v_add_f32_e32 v165, v167, v165
	v_add_f32_e32 v165, v180, v165
	s_waitcnt lgkmcnt(1)
	ds_read2_b64 v[176:179], v164 offset0:196 offset1:198
	v_sub_f32_e32 v173, v229, v166
	v_exp_f32_e32 v204, v173
	v_cvt_pk_bf16_f32 v174, v167, v180
	v_cvt_pk_bf16_f32 v175, v181, v182
	v_mov_b32_e32 v173, v172
	v_add_f32_e32 v165, v181, v165
	v_add_f32_e32 v165, v182, v165
	s_waitcnt lgkmcnt(1)
	v_mfma_f32_32x32x16_bf16 v[18:33], v[168:171], v[172:175], v[18:33]
	ds_read2_b64 v[168:171], v162 offset0:136 offset1:138
	v_add_f32_e32 v165, v183, v165
	v_add_f32_e32 v165, v184, v165
	v_add_f32_e32 v165, v185, v165
	v_add_f32_e32 v165, v186, v165
	v_sub_f32_e32 v203, v235, v166
	v_sub_f32_e32 v167, v234, v166
	s_waitcnt lgkmcnt(1)
	v_mfma_f32_32x32x16_bf16 v[2:17], v[176:179], v[172:175], v[2:17]
	ds_read2_b64 v[176:179], v164 offset0:200 offset1:202
	v_sub_f32_e32 v172, v226, v166
	v_exp_f32_e32 v180, v172
	v_cvt_pk_bf16_f32 v172, v183, v184
	v_cvt_pk_bf16_f32 v173, v185, v186
	v_cvt_pk_bf16_f32 v174, v187, v188
	v_cvt_pk_bf16_f32 v175, v189, v202
	v_add_f32_e32 v165, v187, v165
	v_exp_f32_e32 v203, v203
	s_waitcnt lgkmcnt(1)
	v_mfma_f32_32x32x16_bf16 v[18:33], v[168:171], v[172:175], v[18:33]
	v_sub_f32_e32 v168, v230, v166
	v_exp_f32_e32 v181, v168
	v_sub_f32_e32 v168, v228, v166
	v_exp_f32_e32 v182, v168
	v_sub_f32_e32 v168, v236, v166
	v_exp_f32_e32 v183, v168
	ds_read2_b64 v[168:171], v162 offset0:140 offset1:142
	s_waitcnt lgkmcnt(1)
	v_mfma_f32_32x32x16_bf16 v[2:17], v[176:179], v[172:175], v[2:17]
	ds_read2_b64 v[176:179], v164 offset0:204 offset1:206
	v_sub_f32_e32 v162, v232, v166
	v_exp_f32_e32 v167, v167
	v_exp_f32_e32 v162, v162
	v_add_f32_e32 v165, v188, v165
	v_add_f32_e32 v165, v189, v165
	v_add_f32_e32 v165, v202, v165
	v_add_f32_e32 v165, v203, v165
	v_cvt_pk_bf16_f32 v172, v203, v204
	v_cvt_pk_bf16_f32 v173, v167, v180
	v_cvt_pk_bf16_f32 v174, v181, v182
	v_cvt_pk_bf16_f32 v175, v183, v162
	v_add_f32_e32 v165, v204, v165
	v_add_f32_e32 v164, v167, v165
	s_waitcnt lgkmcnt(1)
	v_mfma_f32_32x32x16_bf16 v[18:33], v[168:171], v[172:175], v[18:33]
	v_add_f32_e32 v164, v180, v164
	v_add_f32_e32 v164, v181, v164
	v_add_f32_e32 v164, v182, v164
	v_add_f32_e32 v164, v183, v164
	v_add_f32_e32 v162, v162, v164
	v_add_f32_e32 v162, v238, v162
	s_waitcnt lgkmcnt(0)
	v_mfma_f32_32x32x16_bf16 v[2:17], v[176:179], v[172:175], v[2:17]
